# lazy softmax reference threshold 8 -> 40 log2 units (p <= 2^40, exact): FoX prompt job no longer rescales every step
# speedup vs baseline: 1.0433x; 1.0025x over previous
.Lj3ld_norka:
	s_or_b64 exec, exec, s[6:7]
	s_waitcnt lgkmcnt(0)
	v_mfma_f32_32x32x16_bf16 v[146:161], v[240:243], v[246:249], v[146:161]
	s_nop 11
	v_pk_add_f32 v[146:147], v[130:131], v[146:147]
	v_pk_add_f32 v[132:133], v[132:133], v[148:149]
	v_max_f32_e32 v130, v146, v147
	v_pk_add_f32 v[134:135], v[134:135], v[150:151]
	v_max3_f32 v130, v130, v132, v133
	v_pk_add_f32 v[136:137], v[136:137], v[152:153]
	v_max3_f32 v130, v130, v134, v135
	v_pk_add_f32 v[138:139], v[138:139], v[154:155]
	v_max3_f32 v130, v130, v136, v137
	v_pk_add_f32 v[140:141], v[140:141], v[156:157]
	v_max3_f32 v130, v130, v138, v139
	v_pk_add_f32 v[142:143], v[142:143], v[158:159]
	v_max3_f32 v130, v130, v140, v141
	v_pk_add_f32 v[144:145], v[144:145], v[160:161]
	v_max3_f32 v130, v130, v142, v143
	v_max3_f32 v130, v130, v144, v145
	v_sub_f32_e32 v131, v230, v130
	v_cmp_gt_f32_e32 vcc, 0xc2200000, v131
	s_cbranch_vccnz .Llazy0_full
	ds_read_b64_tr_b16 v[232:233], v222
	ds_read_b64_tr_b16 v[234:235], v222 offset:4736
	ds_read_b64_tr_b16 v[236:237], v222 offset:64
	ds_read_b64_tr_b16 v[238:239], v222 offset:4800
	ds_read_b64_tr_b16 v[240:241], v222 offset:128
	ds_read_b64_tr_b16 v[242:243], v222 offset:4864
	ds_read_b64_tr_b16 v[246:247], v222 offset:192
	ds_read_b64_tr_b16 v[248:249], v222 offset:4928
	v_mov_b32_e32 v229, v230
	v_mov_b32_e32 v130, 1.0
	s_branch .LBB0_946

.LBB0_954:
	s_or_b64 exec, exec, s[10:11]
	s_cmp_gt_i32 s40, 5
	v_add_u32_e32 v182, v224, v198
	s_cbranch_scc1 .LBB0_958
	ds_read_b128 v[130:133], v182
	ds_read_b128 v[134:137], v223
	ds_read_b128 v[146:149], v182 offset:32
	ds_read_b128 v[150:153], v223 offset:1024
	ds_read_b128 v[184:187], v182 offset:64
	ds_read_b128 v[188:191], v223 offset:2048
	s_waitcnt lgkmcnt(4)
	v_mfma_f32_32x32x16_bf16 v[130:145], v[130:133], v[134:137], 0
	s_waitcnt lgkmcnt(2)
	v_mfma_f32_32x32x16_bf16 v[146:161], v[146:149], v[150:153], 0
	s_waitcnt lgkmcnt(0)
	v_mfma_f32_32x32x16_bf16 v[130:145], v[184:187], v[188:191], v[130:145]
	ds_read_b128 v[184:187], v182 offset:96
	ds_read_b128 v[188:191], v223 offset:3072
	s_waitcnt lgkmcnt(0)
	v_mfma_f32_32x32x16_bf16 v[146:161], v[184:187], v[188:191], v[146:161]
	ds_read_b128 v[184:187], v182 offset:128
	ds_read_b128 v[188:191], v223 offset:4096
	s_waitcnt lgkmcnt(0)
	v_mfma_f32_32x32x16_bf16 v[130:145], v[184:187], v[188:191], v[130:145]
	ds_read_b128 v[184:187], v182 offset:160
	ds_read_b128 v[188:191], v223 offset:5120
	s_waitcnt lgkmcnt(0)
	v_mfma_f32_32x32x16_bf16 v[146:161], v[184:187], v[188:191], v[146:161]
	ds_read_b128 v[184:187], v182 offset:192
	ds_read_b128 v[188:191], v223 offset:6144
	s_waitcnt lgkmcnt(0)
	v_mfma_f32_32x32x16_bf16 v[130:145], v[184:187], v[188:191], v[130:145]
	ds_read_b128 v[184:187], v182 offset:224
	ds_read_b128 v[188:191], v223 offset:7168
	s_waitcnt lgkmcnt(0)
	v_mfma_f32_32x32x16_bf16 v[146:161], v[184:187], v[188:191], v[146:161]
	ds_read_b128 v[184:187], v182 offset:256
	ds_read_b128 v[188:191], v223 offset:8192
	s_waitcnt lgkmcnt(0)
	v_mfma_f32_32x32x16_bf16 v[130:145], v[184:187], v[188:191], v[130:145]
	ds_read_b128 v[184:187], v182 offset:288
	ds_read_b128 v[188:191], v223 offset:9216
	s_waitcnt lgkmcnt(0)
	v_mfma_f32_32x32x16_bf16 v[146:161], v[184:187], v[188:191], v[146:161]
	ds_read_b128 v[184:187], v182 offset:320
	ds_read_b128 v[188:191], v223 offset:10240
	s_waitcnt lgkmcnt(0)
	v_mfma_f32_32x32x16_bf16 v[130:145], v[184:187], v[188:191], v[130:145]
	ds_read_b128 v[184:187], v182 offset:352
	ds_read_b128 v[188:191], v223 offset:11264
	s_waitcnt lgkmcnt(0)
	v_mfma_f32_32x32x16_bf16 v[146:161], v[184:187], v[188:191], v[146:161]
	ds_read_b128 v[184:187], v182 offset:384
	ds_read_b128 v[188:191], v223 offset:12288
	s_waitcnt lgkmcnt(0)
	v_mfma_f32_32x32x16_bf16 v[130:145], v[184:187], v[188:191], v[130:145]
	ds_read_b128 v[184:187], v182 offset:416
	ds_read_b128 v[188:191], v223 offset:13312
	s_waitcnt lgkmcnt(0)
	v_mfma_f32_32x32x16_bf16 v[146:161], v[184:187], v[188:191], v[146:161]
	ds_read_b128 v[184:187], v182 offset:448
	ds_read_b128 v[188:191], v223 offset:14336
	s_waitcnt lgkmcnt(0)
	v_mfma_f32_32x32x16_bf16 v[130:145], v[184:187], v[188:191], v[130:145]
	ds_read_b128 v[184:187], v182 offset:480
	ds_read_b128 v[188:191], v223 offset:15360
	s_waitcnt lgkmcnt(0)
	v_mfma_f32_32x32x16_bf16 v[146:161], v[184:187], v[188:191], v[146:161]
	ds_read_b128 v[184:187], v182 offset:512
	ds_read_b128 v[188:191], v223 offset:16384
	s_waitcnt lgkmcnt(0)
	v_mfma_f32_32x32x16_bf16 v[130:145], v[184:187], v[188:191], v[130:145]
	ds_read_b128 v[184:187], v182 offset:544
	ds_read_b128 v[188:191], v223 offset:17408
	s_waitcnt lgkmcnt(0)
	v_mfma_f32_32x32x16_bf16 v[146:161], v[184:187], v[188:191], v[146:161]
	s_nop 11
	v_pk_add_f32 v[146:147], v[130:131], v[146:147]
	v_pk_add_f32 v[132:133], v[132:133], v[148:149]
	v_max_f32_e32 v130, v146, v147
	v_pk_add_f32 v[134:135], v[134:135], v[150:151]
	v_max3_f32 v130, v130, v132, v133
	v_pk_add_f32 v[136:137], v[136:137], v[152:153]
	v_max3_f32 v130, v130, v134, v135
	v_mbcnt_hi_u32_b32 v131, -1, v217
	v_pk_add_f32 v[138:139], v[138:139], v[154:155]
	v_max3_f32 v130, v130, v136, v137
	v_and_b32_e32 v149, 64, v131
	v_pk_add_f32 v[140:141], v[140:141], v[156:157]
	v_max3_f32 v130, v130, v138, v139
	v_xor_b32_e32 v148, 32, v131
	v_add_u32_e32 v149, 64, v149
	v_pk_add_f32 v[142:143], v[142:143], v[158:159]
	v_max3_f32 v130, v130, v140, v141
	v_cmp_lt_i32_e32 vcc, v148, v149
	v_pk_add_f32 v[144:145], v[144:145], v[160:161]
	v_max3_f32 v130, v130, v142, v143
	v_cndmask_b32_e32 v131, v131, v148, vcc
	v_max3_f32 v130, v130, v144, v145
	v_lshlrev_b32_e32 v131, 2, v131
	ds_bpermute_b32 v131, v131, v130
	s_waitcnt lgkmcnt(0)
	v_max3_f32 v184, v229, v130, v131
	v_sub_f32_e32 v130, v229, v184
	v_cmp_gt_f32_e32 vcc, 0xc2200000, v130
	s_cbranch_vccnz .Llazy1_full
	v_mov_b32_e32 v184, v229
	v_mov_b32_e32 v130, 1.0
	s_branch .LBB0_957

.LBB0_963:
	s_andn2_b64 vcc, exec, s[6:7]
	s_cbranch_vccnz .LBB0_967
	ds_read_b128 v[130:133], v182
	ds_read_b128 v[134:137], v223
	ds_read_b128 v[146:149], v182 offset:32
	ds_read_b128 v[150:153], v223 offset:1024
	ds_read_b128 v[162:165], v182 offset:64
	ds_read_b128 v[166:169], v223 offset:2048
	s_waitcnt lgkmcnt(4)
	v_mfma_f32_32x32x16_bf16 v[130:145], v[130:133], v[134:137], 0
	s_waitcnt lgkmcnt(2)
	v_mfma_f32_32x32x16_bf16 v[146:161], v[146:149], v[150:153], 0
	s_waitcnt lgkmcnt(0)
	v_mfma_f32_32x32x16_bf16 v[130:145], v[162:165], v[166:169], v[130:145]
	ds_read_b128 v[162:165], v182 offset:96
	ds_read_b128 v[166:169], v223 offset:3072
	s_waitcnt lgkmcnt(0)
	v_mfma_f32_32x32x16_bf16 v[146:161], v[162:165], v[166:169], v[146:161]
	ds_read_b128 v[162:165], v182 offset:128
	ds_read_b128 v[166:169], v223 offset:4096
	s_waitcnt lgkmcnt(0)
	v_mfma_f32_32x32x16_bf16 v[130:145], v[162:165], v[166:169], v[130:145]
	ds_read_b128 v[162:165], v182 offset:160
	ds_read_b128 v[166:169], v223 offset:5120
	s_waitcnt lgkmcnt(0)
	v_mfma_f32_32x32x16_bf16 v[146:161], v[162:165], v[166:169], v[146:161]
	ds_read_b128 v[162:165], v182 offset:192
	ds_read_b128 v[166:169], v223 offset:6144
	s_waitcnt lgkmcnt(0)
	v_mfma_f32_32x32x16_bf16 v[130:145], v[162:165], v[166:169], v[130:145]
	ds_read_b128 v[162:165], v182 offset:224
	ds_read_b128 v[166:169], v223 offset:7168
	s_waitcnt lgkmcnt(0)
	v_mfma_f32_32x32x16_bf16 v[146:161], v[162:165], v[166:169], v[146:161]
	ds_read_b128 v[162:165], v182 offset:256
	ds_read_b128 v[166:169], v223 offset:8192
	s_waitcnt lgkmcnt(0)
	v_mfma_f32_32x32x16_bf16 v[130:145], v[162:165], v[166:169], v[130:145]
	ds_read_b128 v[162:165], v182 offset:288
	ds_read_b128 v[166:169], v223 offset:9216
	s_waitcnt lgkmcnt(0)
	v_mfma_f32_32x32x16_bf16 v[146:161], v[162:165], v[166:169], v[146:161]
	ds_read_b128 v[162:165], v182 offset:320
	ds_read_b128 v[166:169], v223 offset:10240
	s_waitcnt lgkmcnt(0)
	v_mfma_f32_32x32x16_bf16 v[130:145], v[162:165], v[166:169], v[130:145]
	ds_read_b128 v[162:165], v182 offset:352
	ds_read_b128 v[166:169], v223 offset:11264
	s_waitcnt lgkmcnt(0)
	v_mfma_f32_32x32x16_bf16 v[146:161], v[162:165], v[166:169], v[146:161]
	ds_read_b128 v[162:165], v182 offset:384
	ds_read_b128 v[166:169], v223 offset:12288
	s_waitcnt lgkmcnt(0)
	v_mfma_f32_32x32x16_bf16 v[130:145], v[162:165], v[166:169], v[130:145]
	ds_read_b128 v[162:165], v182 offset:416
	ds_read_b128 v[166:169], v223 offset:13312
	s_waitcnt lgkmcnt(0)
	v_mfma_f32_32x32x16_bf16 v[146:161], v[162:165], v[166:169], v[146:161]
	ds_read_b128 v[162:165], v182 offset:448
	ds_read_b128 v[166:169], v223 offset:14336
	s_waitcnt lgkmcnt(0)
	v_mfma_f32_32x32x16_bf16 v[130:145], v[162:165], v[166:169], v[130:145]
	ds_read_b128 v[162:165], v182 offset:480
	ds_read_b128 v[166:169], v223 offset:15360
	s_waitcnt lgkmcnt(0)
	v_mfma_f32_32x32x16_bf16 v[146:161], v[162:165], v[166:169], v[146:161]
	ds_read_b128 v[162:165], v182 offset:512
	ds_read_b128 v[166:169], v223 offset:16384
	s_waitcnt lgkmcnt(0)
	v_mfma_f32_32x32x16_bf16 v[130:145], v[162:165], v[166:169], v[130:145]
	ds_read_b128 v[162:165], v182 offset:544
	ds_read_b128 v[166:169], v223 offset:17408
	s_waitcnt lgkmcnt(0)
	v_mfma_f32_32x32x16_bf16 v[146:161], v[162:165], v[166:169], v[146:161]
	s_nop 11
	v_pk_add_f32 v[146:147], v[130:131], v[146:147]
	v_pk_add_f32 v[132:133], v[132:133], v[148:149]
	v_max_f32_e32 v130, v146, v147
	v_pk_add_f32 v[134:135], v[134:135], v[150:151]
	v_max3_f32 v130, v130, v132, v133
	v_pk_add_f32 v[136:137], v[136:137], v[152:153]
	v_max3_f32 v130, v130, v134, v135
	v_pk_add_f32 v[138:139], v[138:139], v[154:155]
	v_max3_f32 v130, v130, v136, v137
	v_and_b32_e32 v131, 64, v218
	v_pk_add_f32 v[140:141], v[140:141], v[156:157]
	v_max3_f32 v130, v130, v138, v139
	v_xor_b32_e32 v149, 32, v218
	v_add_u32_e32 v150, 64, v131
	v_pk_add_f32 v[142:143], v[142:143], v[158:159]
	v_max3_f32 v130, v130, v140, v141
	v_cmp_lt_i32_e32 vcc, v149, v150
	v_pk_add_f32 v[144:145], v[144:145], v[160:161]
	v_max3_f32 v130, v130, v142, v143
	v_cndmask_b32_e32 v131, v218, v149, vcc
	v_max3_f32 v130, v130, v144, v145
	v_lshlrev_b32_e32 v131, 2, v131
	ds_bpermute_b32 v131, v131, v130
	s_waitcnt lgkmcnt(0)
	v_max3_f32 v148, v184, v130, v131
	v_sub_f32_e32 v130, v184, v148
	v_cmp_gt_f32_e32 vcc, 0xc2200000, v130
	s_cbranch_vccnz .Llazy2_full
	v_mov_b32_e32 v148, v184
	v_mov_b32_e32 v130, 1.0
	s_branch .LBB0_966

.LBB0_1005:
	s_nop 0
	v_max3_f32 v64, v171, v169, v52
	v_max3_f32 v64, v64, v166, v53
	v_max3_f32 v64, v64, v167, v168
	v_max3_f32 v64, v64, v170, v54
	v_max3_f32 v64, v64, v164, v55
	v_max3_f32 v64, v64, v165, v56
	v_max3_f32 v64, v64, v162, v57
	v_max3_f32 v64, v64, v163, v58
	v_max3_f32 v64, v64, v160, v59
	v_max3_f32 v64, v64, v161, v60
	v_max3_f32 v64, v64, v158, v61
	v_max3_f32 v64, v64, v159, v62
	v_max3_f32 v64, v64, v156, v63
	v_max3_f32 v64, v64, v157, v50
	v_max3_f32 v64, v64, v154, v51
	v_max_f32_e32 v64, v64, v155
	v_sub_f32_e32 v65, v181, v64
	v_cmp_gt_f32_e32 vcc, 0xc2200000, v65
	s_cbranch_vccnz .Llazy3_full
	s_waitcnt lgkmcnt(0)
	v_mov_b32_e32 v182, v181
	v_mov_b32_e32 v64, 1.0
	s_branch .LBB0_1007

.LBB0_1051:
	s_waitcnt lgkmcnt(0)
	s_nop 3
	s_nop 0
	v_max3_f32 v178, v99, v115, v100
	v_max3_f32 v178, v178, v116, v101
	v_max3_f32 v178, v178, v117, v114
	v_max3_f32 v178, v178, v98, v102
	v_max3_f32 v178, v178, v118, v103
	v_max3_f32 v178, v178, v119, v104
	v_max3_f32 v178, v178, v120, v105
	v_max3_f32 v178, v178, v121, v106
	v_max3_f32 v178, v178, v122, v107
	v_max3_f32 v178, v178, v123, v108
	v_max3_f32 v178, v178, v124, v109
	v_max3_f32 v178, v178, v125, v110
	v_max3_f32 v178, v178, v126, v111
	v_max3_f32 v178, v178, v127, v112
	v_max3_f32 v178, v178, v128, v113
	v_max_f32_e32 v178, v178, v129
	v_sub_f32_e32 v179, v205, v178
	v_cmp_gt_f32_e32 vcc, 0xc2200000, v179
	s_cbranch_vccnz .Llazy4_full
	s_waitcnt lgkmcnt(0)
	v_mov_b32_e32 v207, v205
	v_mov_b32_e32 v178, 1.0
	s_branch .LBB0_1053

.LBB0_1067:
	s_nop 3
	s_nop 0
	v_max3_f32 v114, v83, v67, v84
	v_max3_f32 v114, v114, v68, v85
	v_max3_f32 v114, v114, v69, v66
	v_max3_f32 v114, v114, v82, v86
	v_max3_f32 v114, v114, v70, v87
	v_max3_f32 v114, v114, v71, v88
	v_max3_f32 v114, v114, v72, v89
	v_max3_f32 v114, v114, v73, v90
	v_max3_f32 v114, v114, v74, v91
	v_max3_f32 v114, v114, v75, v92
	v_max3_f32 v114, v114, v76, v93
	v_max3_f32 v114, v114, v77, v94
	v_max3_f32 v114, v114, v78, v95
	v_max3_f32 v114, v114, v79, v96
	v_max3_f32 v114, v114, v80, v97
	v_max_f32_e32 v114, v114, v81
	v_sub_f32_e32 v115, v204, v114
	v_cmp_gt_f32_e32 vcc, 0xc2200000, v115
	s_cbranch_vccnz .Llazy5_full
	s_waitcnt lgkmcnt(0)
	v_mov_b32_e32 v206, v204
	v_mov_b32_e32 v114, 1.0
	s_branch .LBB0_1069

.LBB0_1107:
	s_waitcnt lgkmcnt(0)
	s_nop 3
	s_nop 0
	v_max3_f32 v178, v99, v115, v100
	v_max3_f32 v178, v178, v116, v101
	v_max3_f32 v178, v178, v117, v114
	v_max3_f32 v178, v178, v98, v102
	v_max3_f32 v178, v178, v118, v103
	v_max3_f32 v178, v178, v119, v104
	v_max3_f32 v178, v178, v120, v105
	v_max3_f32 v178, v178, v121, v106
	v_max3_f32 v178, v178, v122, v107
	v_max3_f32 v178, v178, v123, v108
	v_max3_f32 v178, v178, v124, v109
	v_max3_f32 v178, v178, v125, v110
	v_max3_f32 v178, v178, v126, v111
	v_max3_f32 v178, v178, v127, v112
	v_max3_f32 v178, v178, v128, v113
	v_max_f32_e32 v178, v178, v129
	v_sub_f32_e32 v179, v207, v178
	v_cmp_gt_f32_e32 vcc, 0xc2200000, v179
	s_cbranch_vccnz .Llazy6_full
	s_waitcnt lgkmcnt(0)
	v_mov_b32_e32 v205, v207
	v_mov_b32_e32 v178, 1.0
	s_branch .LBB0_1109

.LBB0_1124:
	s_nop 3
	s_nop 0
	v_max3_f32 v114, v83, v67, v84
	v_max3_f32 v114, v114, v68, v85
	v_max3_f32 v114, v114, v69, v66
	v_max3_f32 v114, v114, v82, v86
	v_max3_f32 v114, v114, v70, v87
	v_max3_f32 v114, v114, v71, v88
	v_max3_f32 v114, v114, v72, v89
	v_max3_f32 v114, v114, v73, v90
	v_max3_f32 v114, v114, v74, v91
	v_max3_f32 v114, v114, v75, v92
	v_max3_f32 v114, v114, v76, v93
	v_max3_f32 v114, v114, v77, v94
	v_max3_f32 v114, v114, v78, v95
	v_max3_f32 v114, v114, v79, v96
	v_max3_f32 v114, v114, v80, v97
	v_max_f32_e32 v114, v114, v81
	v_sub_f32_e32 v115, v206, v114
	v_cmp_gt_f32_e32 vcc, 0xc2200000, v115
	s_cbranch_vccnz .Llazy7_full
	s_waitcnt lgkmcnt(0)
	v_mov_b32_e32 v204, v206
	v_mov_b32_e32 v114, 1.0
	s_branch .LBB0_1126

.LBB0_1165:
	s_sub_i32 s45, s42, 64
	s_cmp_ge_u32 s45, s66
	s_cselect_b64 s[48:49], -1, 0
	s_cmp_gt_i32 s44, s39
	s_cselect_b64 s[50:51], -1, 0
	s_or_b64 s[48:49], s[50:51], s[48:49]
	s_and_b64 vcc, exec, s[48:49]
	s_cbranch_vccnz .LBB0_1169
	v_add_u32_e32 v120, v124, v198
	ds_read_b128 v[136:139], v120
	ds_read_b128 v[140:143], v120 offset:6656
	ds_read_b128 v[144:147], v120 offset:32
	ds_read_b128 v[148:151], v120 offset:6688
	ds_read_b128 v[152:155], v120 offset:64
	ds_read_b128 v[156:159], v120 offset:6720
	ds_read_b128 v[160:163], v120 offset:96
	ds_read_b128 v[164:167], v120 offset:6752
	ds_read_b128 v[168:171], v120 offset:128
	ds_read_b128 v[172:175], v120 offset:6784
	ds_read_b128 v[176:179], v120 offset:160
	ds_read_b128 v[180:183], v120 offset:6816
	v_add_u32_e32 v184, v125, v126
	s_waitcnt lgkmcnt(11)
	v_mfma_f32_32x32x16_bf16 v[34:49], v[136:139], v[66:69], 0
	s_waitcnt lgkmcnt(10)
	v_mfma_f32_32x32x16_bf16 v[50:65], v[140:143], v[66:69], 0
	s_waitcnt lgkmcnt(9)
	v_mfma_f32_32x32x16_bf16 v[34:49], v[144:147], v[70:73], v[34:49]
	s_waitcnt lgkmcnt(8)
	v_mfma_f32_32x32x16_bf16 v[50:65], v[148:151], v[70:73], v[50:65]
	s_waitcnt lgkmcnt(7)
	v_mfma_f32_32x32x16_bf16 v[34:49], v[152:155], v[74:77], v[34:49]
	s_waitcnt lgkmcnt(6)
	v_mfma_f32_32x32x16_bf16 v[50:65], v[156:159], v[74:77], v[50:65]
	s_waitcnt lgkmcnt(5)
	v_mfma_f32_32x32x16_bf16 v[34:49], v[160:163], v[78:81], v[34:49]
	s_waitcnt lgkmcnt(4)
	v_mfma_f32_32x32x16_bf16 v[50:65], v[164:167], v[78:81], v[50:65]
	s_waitcnt lgkmcnt(3)
	v_mfma_f32_32x32x16_bf16 v[34:49], v[168:171], v[106:109], v[34:49]
	s_waitcnt lgkmcnt(2)
	v_mfma_f32_32x32x16_bf16 v[50:65], v[172:175], v[106:109], v[50:65]
	s_waitcnt lgkmcnt(1)
	v_mfma_f32_32x32x16_bf16 v[34:49], v[176:179], v[110:113], v[34:49]
	s_waitcnt lgkmcnt(0)
	v_mfma_f32_32x32x16_bf16 v[50:65], v[180:183], v[110:113], v[50:65]
	s_nop 11
	v_max3_f32 v120, v34, v35, v36
	v_max3_f32 v120, v120, v37, v38
	v_max3_f32 v120, v120, v39, v40
	v_max3_f32 v120, v120, v41, v42
	v_max3_f32 v120, v120, v43, v44
	v_max3_f32 v120, v120, v45, v46
	v_max3_f32 v120, v120, v47, v48
	v_max3_f32 v120, v120, v49, v50
	v_max3_f32 v120, v120, v51, v52
	v_max3_f32 v120, v120, v53, v54
	v_max3_f32 v120, v120, v55, v56
	v_max3_f32 v120, v120, v57, v58
	v_max3_f32 v120, v120, v59, v60
	v_max3_f32 v120, v120, v61, v62
	v_max3_f32 v120, v120, v63, v64
	v_max_f32_e32 v120, v120, v65
	v_sub_f32_e32 v130, v129, v120
	v_cmp_gt_f32_e32 vcc, 0xc2200000, v130
	s_cbranch_vccnz .Llazy8_full
	ds_read_b64_tr_b16 v[136:137], v184 offset:13312
	ds_read_b64_tr_b16 v[138:139], v184 offset:14464
	ds_read_b64_tr_b16 v[140:141], v184 offset:13376
	ds_read_b64_tr_b16 v[142:143], v184 offset:14528
	ds_read_b64_tr_b16 v[144:145], v184 offset:15616
	ds_read_b64_tr_b16 v[146:147], v184 offset:16768
	ds_read_b64_tr_b16 v[148:149], v184 offset:15680
	ds_read_b64_tr_b16 v[150:151], v184 offset:16832
	ds_read_b64_tr_b16 v[152:153], v184 offset:17920
	ds_read_b64_tr_b16 v[154:155], v184 offset:19072
	ds_read_b64_tr_b16 v[156:157], v184 offset:17984
	ds_read_b64_tr_b16 v[158:159], v184 offset:19136
	ds_read_b64_tr_b16 v[160:161], v184 offset:20224
	ds_read_b64_tr_b16 v[162:163], v184 offset:21376
	ds_read_b64_tr_b16 v[164:165], v184 offset:20288
	ds_read_b64_tr_b16 v[166:167], v184 offset:21440
	v_mov_b32_e32 v130, v129
	v_mov_b32_e32 v120, 1.0
	s_branch .LBB0_1168

.LBB0_1179:
	s_cmp_ge_u32 s42, s66
	s_cselect_b64 s[48:49], -1, 0
	s_cmp_ge_i32 s44, s39
	s_cselect_b64 s[50:51], -1, 0
	s_or_b64 s[48:49], s[50:51], s[48:49]
	s_and_b64 vcc, exec, s[48:49]
	s_cbranch_vccnz .LBB0_1184
	v_add_u32_e32 v120, v124, v198
	ds_read_b128 v[136:139], v120 offset:32768
	ds_read_b128 v[140:143], v120 offset:39424
	ds_read_b128 v[144:147], v120 offset:32800
	ds_read_b128 v[148:151], v120 offset:39456
	ds_read_b128 v[152:155], v120 offset:32832
	ds_read_b128 v[156:159], v120 offset:39488
	ds_read_b128 v[160:163], v120 offset:32864
	ds_read_b128 v[164:167], v120 offset:39520
	ds_read_b128 v[168:171], v120 offset:32896
	ds_read_b128 v[172:175], v120 offset:39552
	ds_read_b128 v[176:179], v120 offset:32928
	ds_read_b128 v[180:183], v120 offset:39584
	v_add_u32_e32 v184, v125, v126
	s_waitcnt lgkmcnt(11)
	v_mfma_f32_32x32x16_bf16 v[34:49], v[136:139], v[66:69], 0
	s_waitcnt lgkmcnt(10)
	v_mfma_f32_32x32x16_bf16 v[50:65], v[140:143], v[66:69], 0
	s_waitcnt lgkmcnt(9)
	v_mfma_f32_32x32x16_bf16 v[34:49], v[144:147], v[70:73], v[34:49]
	s_waitcnt lgkmcnt(8)
	v_mfma_f32_32x32x16_bf16 v[50:65], v[148:151], v[70:73], v[50:65]
	s_waitcnt lgkmcnt(7)
	v_mfma_f32_32x32x16_bf16 v[34:49], v[152:155], v[74:77], v[34:49]
	s_waitcnt lgkmcnt(6)
	v_mfma_f32_32x32x16_bf16 v[50:65], v[156:159], v[74:77], v[50:65]
	s_waitcnt lgkmcnt(5)
	v_mfma_f32_32x32x16_bf16 v[34:49], v[160:163], v[78:81], v[34:49]
	s_waitcnt lgkmcnt(4)
	v_mfma_f32_32x32x16_bf16 v[50:65], v[164:167], v[78:81], v[50:65]
	s_waitcnt lgkmcnt(3)
	v_mfma_f32_32x32x16_bf16 v[34:49], v[168:171], v[106:109], v[34:49]
	s_waitcnt lgkmcnt(2)
	v_mfma_f32_32x32x16_bf16 v[50:65], v[172:175], v[106:109], v[50:65]
	s_waitcnt lgkmcnt(1)
	v_mfma_f32_32x32x16_bf16 v[34:49], v[176:179], v[110:113], v[34:49]
	s_waitcnt lgkmcnt(0)
	v_mfma_f32_32x32x16_bf16 v[50:65], v[180:183], v[110:113], v[50:65]
	s_nop 11
	v_max3_f32 v120, v34, v35, v36
	v_max3_f32 v120, v120, v37, v38
	v_max3_f32 v120, v120, v39, v40
	v_max3_f32 v120, v120, v41, v42
	v_max3_f32 v120, v120, v43, v44
	v_max3_f32 v120, v120, v45, v46
	v_max3_f32 v120, v120, v47, v48
	v_max3_f32 v120, v120, v49, v50
	v_max3_f32 v120, v120, v51, v52
	v_max3_f32 v120, v120, v53, v54
	v_max3_f32 v120, v120, v55, v56
	v_max3_f32 v120, v120, v57, v58
	v_max3_f32 v120, v120, v59, v60
	v_max3_f32 v120, v120, v61, v62
	v_max3_f32 v120, v120, v63, v64
	v_max_f32_e32 v120, v120, v65
	v_sub_f32_e32 v129, v130, v120
	v_cmp_gt_f32_e32 vcc, 0xc2200000, v129
	s_cbranch_vccnz .Llazy9_full
	ds_read_b64_tr_b16 v[136:137], v184 offset:46080
	ds_read_b64_tr_b16 v[138:139], v184 offset:47232
	ds_read_b64_tr_b16 v[140:141], v184 offset:46144
	ds_read_b64_tr_b16 v[142:143], v184 offset:47296
	ds_read_b64_tr_b16 v[144:145], v184 offset:48384
	ds_read_b64_tr_b16 v[146:147], v184 offset:49536
	ds_read_b64_tr_b16 v[148:149], v184 offset:48448
	ds_read_b64_tr_b16 v[150:151], v184 offset:49600
	ds_read_b64_tr_b16 v[152:153], v184 offset:50688
	ds_read_b64_tr_b16 v[154:155], v184 offset:51840
	ds_read_b64_tr_b16 v[156:157], v184 offset:50752
	ds_read_b64_tr_b16 v[158:159], v184 offset:51904
	ds_read_b64_tr_b16 v[160:161], v184 offset:52992
	ds_read_b64_tr_b16 v[162:163], v184 offset:54144
	ds_read_b64_tr_b16 v[164:165], v184 offset:53056
	ds_read_b64_tr_b16 v[166:167], v184 offset:54208
	v_mov_b32_e32 v129, v130
	v_mov_b32_e32 v120, 1.0
	s_branch .LBB0_1182
